# cross-attention step rescheduled (LDS fragments read ahead), task order permuted so tiles of one batch-head share an XCD
# speedup vs baseline: 1.0457x; 1.0068x over previous
.LBB0_2491:
	s_and_b32 s76, s18, 0xffffff00
	s_and_b32 s77, s18, 7
	s_lshl_b32 s77, s77, 5
	s_or_b32 s76, s76, s77
	s_bfe_u32 s77, s18, 0x10007
	s_lshl_b32 s77, s77, 4
	s_or_b32 s76, s76, s77
	s_bfe_u32 s77, s18, 0x40003
	s_or_b32 s76, s76, s77
	s_lshl_b32 s6, s76, 7
	s_ashr_i32 s14, s76, 6
	s_and_b32 s6, s6, 0x780
	s_ashr_i32 s15, s14, 31
	v_add_u32_e32 v138, s6, v137
	s_bfe_u32 s24, s76, 0x20004
	s_lshl_b64 s[20:21], s[14:15], 21
	v_lshlrev_b64 v[0:1], 10, v[138:139]
	v_lshl_add_u64 v[184:185], s[20:21], 0, v[0:1]
	s_lshl_b32 s19, s24, 8
	s_lshl_b32 s6, s24, 9
	s_lshl_b64 s[20:21], s[14:15], 19
	s_add_u32 s15, s9, s20
	v_lshl_add_u64 v[0:1], v[184:185], 1, s[2:3]
	s_addc_u32 s23, s16, s21
	v_lshl_add_u64 v[0:1], v[0:1], 0, s[6:7]
	v_mov_b32_e32 v163, v139
	s_add_u32 s22, s15, s6
	v_lshl_add_u64 v[0:1], v[0:1], 0, v[162:163]
	s_addc_u32 s23, s23, 0
	s_lshl_b32 s14, s14, 2
	s_or_b32 s14, s14, s24
	global_load_dwordx4 v[20:23], v[0:1], off
	global_load_dwordx4 v[24:27], v[0:1], off offset:64
	global_load_dwordx4 v[28:31], v[0:1], off offset:128
	global_load_dwordx4 v[32:35], v[0:1], off offset:192
	global_load_dwordx4 v[36:39], v[0:1], off offset:256
	global_load_dwordx4 v[44:47], v[0:1], off offset:320
	global_load_dwordx4 v[48:51], v[0:1], off offset:384
	global_load_dwordx4 v[52:55], v[0:1], off offset:448
	s_ashr_i32 s15, s14, 31
	v_mov_b32_e32 v165, v139
	s_lshl_b64 s[14:15], s[14:15], 17
	v_lshl_add_u64 v[0:1], s[22:23], 0, v[164:165]
	v_mov_b32_e32 v167, v139
	v_lshl_add_u64 v[2:3], v[142:143], 0, s[14:15]
	v_lshl_add_u64 v[4:5], v[0:1], 0, v[166:167]
	v_mov_b32_e32 v169, v139
	v_mov_b32_e32 v171, v139
	v_lshl_add_u64 v[6:7], v[2:3], 0, v[168:169]
	global_load_dwordx4 v[60:63], v[4:5], off
	global_load_dwordx4 v[64:67], v[6:7], off
	v_lshl_add_u64 v[4:5], v[0:1], 0, v[170:171]
	v_mov_b32_e32 v173, v139
	v_mov_b32_e32 v175, v139
	v_mov_b32_e32 v179, v139
	v_lshl_add_u64 v[6:7], v[2:3], 0, v[172:173]
	global_load_dwordx4 v[72:75], v[4:5], off
	global_load_dwordx4 v[80:83], v[6:7], off
	v_lshl_add_u64 v[4:5], v[0:1], 0, v[174:175]
	v_mov_b32_e32 v177, v139
	v_lshl_add_u64 v[0:1], v[0:1], 0, v[178:179]
	v_mov_b32_e32 v181, v139
	v_lshl_add_u64 v[6:7], v[2:3], 0, v[176:177]
	global_load_dwordx4 v[84:87], v[4:5], off
	global_load_dwordx4 v[88:91], v[6:7], off
	v_lshl_add_u64 v[2:3], v[2:3], 0, v[180:181]
	global_load_dwordx4 v[100:103], v[0:1], off
	global_load_dwordx4 v[104:107], v[2:3], off
	s_or_b32 s20, s20, s6
	v_lshl_add_u64 v[186:187], v[144:145], 0, s[14:15]
	v_lshl_add_u64 v[188:189], v[146:147], 0, s[14:15]
	v_lshl_add_u64 v[190:191], v[148:149], 0, s[14:15]
	v_lshl_add_u64 v[192:193], v[150:151], 0, s[14:15]
	v_lshl_add_u64 v[194:195], s[20:21], 0, v[154:155]
	v_lshl_add_u64 v[196:197], s[20:21], 0, v[156:157]
	v_lshl_add_u64 v[198:199], s[20:21], 0, v[158:159]
	v_lshl_add_u64 v[200:201], s[20:21], 0, v[160:161]
	v_mov_b32_e32 v128, 0xf149f2ca
	s_mov_b64 s[14:15], 0
	s_mov_b32 s6, 4
	v_mov_b32_e32 v163, 0
	v_mov_b32_e32 v0, 0
	v_mov_b32_e32 v1, v139
	v_mov_b32_e32 v2, v139
	v_mov_b32_e32 v3, v139
	v_mov_b32_e32 v4, 0
	v_mov_b32_e32 v5, v139
	v_mov_b32_e32 v6, v139
	v_mov_b32_e32 v7, v139
	v_mov_b32_e32 v8, 0
	v_mov_b32_e32 v9, v139
	v_mov_b32_e32 v10, v139
	v_mov_b32_e32 v11, v139
	v_mov_b32_e32 v12, 0
	v_mov_b32_e32 v13, v139
	v_mov_b32_e32 v14, v139
	v_mov_b32_e32 v15, v139
	v_mov_b32_e32 v16, 0
	v_mov_b32_e32 v17, v139
	v_mov_b32_e32 v18, v139
	v_mov_b32_e32 v19, v139
	v_mov_b32_e32 v40, 0
	v_mov_b32_e32 v41, v139
	s_waitcnt vmcnt(0)
	v_mov_b32_e32 v42, v139
	v_mov_b32_e32 v43, v139
	v_mov_b32_e32 v56, 0
	v_mov_b32_e32 v57, v139
	v_mov_b32_e32 v58, v139
	v_mov_b32_e32 v59, v139
	v_mov_b32_e32 v68, 0
	v_mov_b32_e32 v69, v139
	v_mov_b32_e32 v70, v139
	v_mov_b32_e32 v71, v139
	v_mov_b32_e32 v76, 0
	v_mov_b32_e32 v77, v139
	v_mov_b32_e32 v78, v139
	v_mov_b32_e32 v79, v139
	v_mov_b32_e32 v92, 0
	v_mov_b32_e32 v93, v139
	v_mov_b32_e32 v94, v139
	v_mov_b32_e32 v95, v139
	v_mov_b32_e32 v96, 0
	v_mov_b32_e32 v97, v139
	v_mov_b32_e32 v98, v139
	v_mov_b32_e32 v99, v139
	v_mov_b32_e32 v108, 0
	v_mov_b32_e32 v109, v139
	v_mov_b32_e32 v110, v139
	v_mov_b32_e32 v111, v139
	v_mov_b32_e32 v112, 0
	v_mov_b32_e32 v113, v139
	v_mov_b32_e32 v114, v139
	v_mov_b32_e32 v115, v139
	v_mov_b32_e32 v116, 0
	v_mov_b32_e32 v117, v139
	v_mov_b32_e32 v118, v139
	v_mov_b32_e32 v119, v139
	v_mov_b32_e32 v120, 0
	v_mov_b32_e32 v121, v139
	v_mov_b32_e32 v122, v139
	v_mov_b32_e32 v123, v139
	v_mov_b32_e32 v124, 0
	v_mov_b32_e32 v125, v139
	v_mov_b32_e32 v126, v139
	v_mov_b32_e32 v127, v139

.LBB0_2494:
	v_add3_u32 v244, s20, v203, v213
	v_add3_u32 v245, s20, v203, v214
	v_add3_u32 v219, s20, v136, v204
	v_mov_b32_e32 v175, v128
	s_xor_b64 s[14:15], s[14:15], -1
	s_add_i32 s6, s6, -1
	ds_read_b128 v[220:223], v244 offset:0
	ds_read_b128 v[224:227], v244 offset:64
	ds_read_b128 v[228:231], v244 offset:128
	ds_read_b128 v[232:235], v244 offset:192
	v_add_u32_e32 v219, 0x8400, v219
	s_waitcnt lgkmcnt(3)
	v_mfma_f32_16x16x32_bf16 v[236:239], v[220:223], v[20:23], 0
	ds_read_b128 v[220:223], v244 offset:256
	s_waitcnt lgkmcnt(3)
	v_mfma_f32_16x16x32_bf16 v[236:239], v[224:227], v[24:27], v[236:239]
	ds_read_b128 v[224:227], v244 offset:320
	v_lshl_add_u64 v[186:187], v[186:187], 0, s[10:11]
	s_waitcnt lgkmcnt(3)
	v_mfma_f32_16x16x32_bf16 v[236:239], v[228:231], v[28:31], v[236:239]
	ds_read_b128 v[228:231], v244 offset:384
	s_waitcnt lgkmcnt(3)
	v_mfma_f32_16x16x32_bf16 v[236:239], v[232:235], v[32:35], v[236:239]
	ds_read_b128 v[232:235], v244 offset:448
	v_lshl_add_u64 v[188:189], v[188:189], 0, s[10:11]
	s_waitcnt lgkmcnt(3)
	v_mfma_f32_16x16x32_bf16 v[236:239], v[220:223], v[36:39], v[236:239]
	ds_read_b128 v[220:223], v244 offset:8448
	s_waitcnt lgkmcnt(3)
	v_mfma_f32_16x16x32_bf16 v[236:239], v[224:227], v[44:47], v[236:239]
	ds_read_b128 v[224:227], v244 offset:8512
	v_lshl_add_u64 v[190:191], v[190:191], 0, s[10:11]
	s_waitcnt lgkmcnt(3)
	v_mfma_f32_16x16x32_bf16 v[236:239], v[228:231], v[48:51], v[236:239]
	ds_read_b128 v[228:231], v244 offset:8576
	s_waitcnt lgkmcnt(3)
	v_mfma_f32_16x16x32_bf16 v[236:239], v[232:235], v[52:55], v[236:239]
	ds_read_b128 v[232:235], v244 offset:8640
	v_lshl_add_u64 v[192:193], v[192:193], 0, s[10:11]
	s_waitcnt lgkmcnt(3)
	v_mfma_f32_16x16x32_bf16 v[240:243], v[220:223], v[20:23], 0
	ds_read_b128 v[220:223], v244 offset:8704
	s_waitcnt lgkmcnt(3)
	v_mfma_f32_16x16x32_bf16 v[240:243], v[224:227], v[24:27], v[240:243]
	ds_read_b128 v[224:227], v244 offset:8768
	v_lshl_add_u64 v[194:195], v[194:195], 0, s[12:13]
	s_waitcnt lgkmcnt(3)
	v_mfma_f32_16x16x32_bf16 v[240:243], v[228:231], v[28:31], v[240:243]
	ds_read_b128 v[228:231], v244 offset:8832
	s_waitcnt lgkmcnt(3)
	v_mfma_f32_16x16x32_bf16 v[240:243], v[232:235], v[32:35], v[240:243]
	ds_read_b128 v[232:235], v244 offset:8896
	v_lshl_add_u64 v[196:197], v[196:197], 0, s[12:13]
	s_waitcnt lgkmcnt(3)
	v_mfma_f32_16x16x32_bf16 v[240:243], v[220:223], v[36:39], v[240:243]
	ds_read_b128 v[220:223], v244 offset:16896
	v_pk_mul_f32 v[236:237], v[236:237], s[8:9] op_sel_hi:[1,0]
	v_pk_mul_f32 v[238:239], v[238:239], s[8:9] op_sel_hi:[1,0]
	s_waitcnt lgkmcnt(3)
	v_mfma_f32_16x16x32_bf16 v[240:243], v[224:227], v[44:47], v[240:243]
	ds_read_b128 v[224:227], v244 offset:16960
	v_lshl_add_u64 v[198:199], v[198:199], 0, s[12:13]
	s_waitcnt lgkmcnt(3)
	v_mfma_f32_16x16x32_bf16 v[240:243], v[228:231], v[48:51], v[240:243]
	ds_read_b128 v[228:231], v244 offset:17024
	s_waitcnt lgkmcnt(3)
	v_mfma_f32_16x16x32_bf16 v[240:243], v[232:235], v[52:55], v[240:243]
	ds_read_b128 v[232:235], v244 offset:17088
	v_lshl_add_u64 v[200:201], v[200:201], 0, s[12:13]
	s_waitcnt lgkmcnt(3)
	v_mfma_f32_16x16x32_bf16 v[128:131], v[220:223], v[20:23], 0
	ds_read_b128 v[220:223], v244 offset:17152
	s_waitcnt lgkmcnt(3)
	v_mfma_f32_16x16x32_bf16 v[128:131], v[224:227], v[24:27], v[128:131]
	ds_read_b128 v[224:227], v244 offset:17216
	s_waitcnt lgkmcnt(3)
	v_mfma_f32_16x16x32_bf16 v[128:131], v[228:231], v[28:31], v[128:131]
	ds_read_b128 v[228:231], v244 offset:17280
	s_waitcnt lgkmcnt(3)
	v_mfma_f32_16x16x32_bf16 v[128:131], v[232:235], v[32:35], v[128:131]
	ds_read_b128 v[232:235], v244 offset:17344
	s_waitcnt lgkmcnt(3)
	v_mfma_f32_16x16x32_bf16 v[128:131], v[220:223], v[36:39], v[128:131]
	ds_read_b128 v[220:223], v245 offset:0
	v_pk_mul_f32 v[240:241], v[240:241], s[8:9] op_sel_hi:[1,0]
	v_pk_mul_f32 v[242:243], v[242:243], s[8:9] op_sel_hi:[1,0]
	s_waitcnt lgkmcnt(3)
	v_mfma_f32_16x16x32_bf16 v[128:131], v[224:227], v[44:47], v[128:131]
	ds_read_b128 v[224:227], v245 offset:64
	s_waitcnt lgkmcnt(3)
	v_mfma_f32_16x16x32_bf16 v[128:131], v[228:231], v[48:51], v[128:131]
	ds_read_b128 v[228:231], v245 offset:128
	s_waitcnt lgkmcnt(3)
	v_mfma_f32_16x16x32_bf16 v[128:131], v[232:235], v[52:55], v[128:131]
	ds_read_b128 v[232:235], v245 offset:192
	s_waitcnt lgkmcnt(3)
	v_mfma_f32_16x16x32_bf16 v[132:135], v[220:223], v[20:23], 0
	ds_read_b128 v[220:223], v245 offset:256
	s_waitcnt lgkmcnt(3)
	v_mfma_f32_16x16x32_bf16 v[132:135], v[224:227], v[24:27], v[132:135]
	ds_read_b128 v[224:227], v245 offset:320
	s_waitcnt lgkmcnt(3)
	v_mfma_f32_16x16x32_bf16 v[132:135], v[228:231], v[28:31], v[132:135]
	ds_read_b128 v[228:231], v245 offset:384
	s_waitcnt lgkmcnt(3)
	v_mfma_f32_16x16x32_bf16 v[132:135], v[232:235], v[32:35], v[132:135]
	ds_read_b128 v[232:235], v245 offset:448
	s_waitcnt lgkmcnt(3)
	v_mfma_f32_16x16x32_bf16 v[132:135], v[220:223], v[36:39], v[132:135]
	v_pk_mul_f32 v[128:129], v[128:129], s[8:9] op_sel_hi:[1,0]
	v_pk_mul_f32 v[130:131], v[130:131], s[8:9] op_sel_hi:[1,0]
	s_waitcnt lgkmcnt(2)
	v_mfma_f32_16x16x32_bf16 v[132:135], v[224:227], v[44:47], v[132:135]
	s_waitcnt lgkmcnt(1)
	v_mfma_f32_16x16x32_bf16 v[132:135], v[228:231], v[48:51], v[132:135]
	s_waitcnt lgkmcnt(0)
	v_mfma_f32_16x16x32_bf16 v[132:135], v[232:235], v[52:55], v[132:135]
	ds_read_b64 v[228:229], v219 offset:0
	ds_read_b64 v[230:231], v219 offset:32
	ds_read_b64 v[232:233], v219 offset:64
	ds_read_b64 v[234:235], v219 offset:96
	s_nop 3
	v_pk_mul_f32 v[132:133], v[132:133], s[8:9] op_sel_hi:[1,0]
	v_pk_mul_f32 v[134:135], v[134:135], s[8:9] op_sel_hi:[1,0]
	v_max3_f32 v167, v236, v237, v238
	v_max3_f32 v167, v167, v239, v240
	v_max3_f32 v167, v167, v241, v242
	v_max3_f32 v167, v167, v243, v128
	v_max3_f32 v167, v167, v129, v130
	v_max3_f32 v167, v167, v131, v132
	v_max3_f32 v167, v167, v133, v134
	v_max3_f32 v167, v167, s17, v135
	v_mov_b32_e32 v169, v167
	s_nop 1
	v_permlane16_swap_b32_e32 v167, v169
	v_max_f32_e32 v169, v169, v169
	v_max_f32_e32 v167, v167, v167
	v_max_f32_e32 v167, v167, v169
	v_mov_b32_e32 v169, v167
	s_nop 1
	v_permlane32_swap_b32_e32 v167, v169
	v_max3_f32 v165, v175, v167, v169
	v_sub_f32_e32 v173, v175, v165
	v_mul_f32_e32 v173, 0x3fb8aa3b, v173
	v_exp_f32_e32 v138, v173
	v_sub_f32_e32 v236, v236, v165
	v_sub_f32_e32 v237, v237, v165
	v_sub_f32_e32 v238, v238, v165
	v_sub_f32_e32 v239, v239, v165
	v_sub_f32_e32 v240, v240, v165
	v_sub_f32_e32 v241, v241, v165
	v_sub_f32_e32 v242, v242, v165
	v_sub_f32_e32 v243, v243, v165
	v_sub_f32_e32 v128, v128, v165
	v_sub_f32_e32 v129, v129, v165
	v_sub_f32_e32 v130, v130, v165
	v_sub_f32_e32 v131, v131, v165
	v_sub_f32_e32 v132, v132, v165
	v_sub_f32_e32 v133, v133, v165
	v_sub_f32_e32 v134, v134, v165
	v_sub_f32_e32 v135, v135, v165
	v_mul_f32_e32 v236, 0x3fb8aa3b, v236
	v_mul_f32_e32 v237, 0x3fb8aa3b, v237
	v_mul_f32_e32 v238, 0x3fb8aa3b, v238
	v_mul_f32_e32 v239, 0x3fb8aa3b, v239
	v_mul_f32_e32 v240, 0x3fb8aa3b, v240
	v_mul_f32_e32 v241, 0x3fb8aa3b, v241
	v_mul_f32_e32 v242, 0x3fb8aa3b, v242
	v_mul_f32_e32 v243, 0x3fb8aa3b, v243
	v_mul_f32_e32 v128, 0x3fb8aa3b, v128
	v_mul_f32_e32 v129, 0x3fb8aa3b, v129
	v_mul_f32_e32 v130, 0x3fb8aa3b, v130
	v_mul_f32_e32 v131, 0x3fb8aa3b, v131
	v_mul_f32_e32 v132, 0x3fb8aa3b, v132
	v_mul_f32_e32 v133, 0x3fb8aa3b, v133
	v_mul_f32_e32 v134, 0x3fb8aa3b, v134
	v_mul_f32_e32 v135, 0x3fb8aa3b, v135
	v_exp_f32_e32 v236, v236
	v_exp_f32_e32 v237, v237
	v_exp_f32_e32 v238, v238
	v_exp_f32_e32 v239, v239
	v_exp_f32_e32 v240, v240
	v_exp_f32_e32 v241, v241
	v_exp_f32_e32 v242, v242
	v_exp_f32_e32 v243, v243
	v_exp_f32_e32 v128, v128
	v_exp_f32_e32 v129, v129
	v_exp_f32_e32 v130, v130
	v_exp_f32_e32 v131, v131
	v_exp_f32_e32 v132, v132
	v_exp_f32_e32 v133, v133
	v_exp_f32_e32 v134, v134
	v_exp_f32_e32 v135, v135
	v_pk_mul_f32 v[124:125], v[124:125], v[138:139] op_sel_hi:[1,0]
	v_pk_mul_f32 v[126:127], v[126:127], v[138:139] op_sel_hi:[1,0]
	v_pk_mul_f32 v[120:121], v[120:121], v[138:139] op_sel_hi:[1,0]
	v_pk_mul_f32 v[122:123], v[122:123], v[138:139] op_sel_hi:[1,0]
	v_pk_mul_f32 v[116:117], v[116:117], v[138:139] op_sel_hi:[1,0]
	v_pk_mul_f32 v[118:119], v[118:119], v[138:139] op_sel_hi:[1,0]
	v_pk_mul_f32 v[112:113], v[112:113], v[138:139] op_sel_hi:[1,0]
	v_pk_mul_f32 v[114:115], v[114:115], v[138:139] op_sel_hi:[1,0]
	v_pk_mul_f32 v[108:109], v[108:109], v[138:139] op_sel_hi:[1,0]
	v_pk_mul_f32 v[110:111], v[110:111], v[138:139] op_sel_hi:[1,0]
	v_pk_mul_f32 v[96:97], v[96:97], v[138:139] op_sel_hi:[1,0]
	v_pk_mul_f32 v[98:99], v[98:99], v[138:139] op_sel_hi:[1,0]
	v_pk_mul_f32 v[92:93], v[92:93], v[138:139] op_sel_hi:[1,0]
	v_pk_mul_f32 v[94:95], v[94:95], v[138:139] op_sel_hi:[1,0]
	v_pk_mul_f32 v[76:77], v[76:77], v[138:139] op_sel_hi:[1,0]
	v_pk_mul_f32 v[78:79], v[78:79], v[138:139] op_sel_hi:[1,0]
	v_pk_mul_f32 v[68:69], v[68:69], v[138:139] op_sel_hi:[1,0]
	v_pk_mul_f32 v[70:71], v[70:71], v[138:139] op_sel_hi:[1,0]
	v_pk_mul_f32 v[56:57], v[56:57], v[138:139] op_sel_hi:[1,0]
	v_pk_mul_f32 v[58:59], v[58:59], v[138:139] op_sel_hi:[1,0]
	v_pk_mul_f32 v[40:41], v[40:41], v[138:139] op_sel_hi:[1,0]
	v_pk_mul_f32 v[42:43], v[42:43], v[138:139] op_sel_hi:[1,0]
	v_pk_mul_f32 v[16:17], v[16:17], v[138:139] op_sel_hi:[1,0]
	v_pk_mul_f32 v[18:19], v[18:19], v[138:139] op_sel_hi:[1,0]
	v_pk_mul_f32 v[12:13], v[12:13], v[138:139] op_sel_hi:[1,0]
	v_pk_mul_f32 v[14:15], v[14:15], v[138:139] op_sel_hi:[1,0]
	v_pk_mul_f32 v[8:9], v[8:9], v[138:139] op_sel_hi:[1,0]
	v_pk_mul_f32 v[10:11], v[10:11], v[138:139] op_sel_hi:[1,0]
	v_pk_mul_f32 v[4:5], v[4:5], v[138:139] op_sel_hi:[1,0]
	v_pk_mul_f32 v[6:7], v[6:7], v[138:139] op_sel_hi:[1,0]
	v_pk_mul_f32 v[0:1], v[0:1], v[138:139] op_sel_hi:[1,0]
	v_pk_mul_f32 v[2:3], v[2:3], v[138:139] op_sel_hi:[1,0]
	v_add_f32_e32 v171, 0, v236
	v_add_f32_e32 v171, v237, v171
	v_add_f32_e32 v171, v238, v171
	v_add_f32_e32 v171, v239, v171
	v_add_f32_e32 v171, v240, v171
	v_add_f32_e32 v171, v241, v171
	v_add_f32_e32 v171, v242, v171
	v_add_f32_e32 v171, v243, v171
	v_add_f32_e32 v171, v128, v171
	v_add_f32_e32 v171, v129, v171
	v_add_f32_e32 v171, v130, v171
	v_add_f32_e32 v171, v131, v171
	v_add_f32_e32 v171, v132, v171
	v_add_f32_e32 v171, v133, v171
	v_add_f32_e32 v171, v134, v171
	v_add_f32_e32 v171, v135, v171
	v_cvt_pk_bf16_f32 v220, v236, v237
	v_cvt_pk_bf16_f32 v221, v238, v239
	v_cvt_pk_bf16_f32 v222, v240, v241
	v_cvt_pk_bf16_f32 v223, v242, v243
	v_cvt_pk_bf16_f32 v224, v128, v129
	v_cvt_pk_bf16_f32 v225, v130, v131
	v_cvt_pk_bf16_f32 v226, v132, v133
	v_cvt_pk_bf16_f32 v227, v134, v135
	v_fmac_f32_e32 v171, v163, v138
	ds_read_b64 v[236:237], v219 offset:2304
	ds_read_b64 v[238:239], v219 offset:2336
	ds_read_b64 v[240:241], v219 offset:2368
	ds_read_b64 v[242:243], v219 offset:2400
	ds_read_b64 v[128:129], v219 offset:4608
	ds_read_b64 v[130:131], v219 offset:4640
	ds_read_b64 v[132:133], v219 offset:4672
	ds_read_b64 v[134:135], v219 offset:4704
	s_waitcnt lgkmcnt(10)
	s_nop 0
	v_mfma_f32_16x16x32_bf16 v[124:127], v[228:231], v[220:223], v[124:127]
	ds_read_b64 v[228:229], v219 offset:6912
	ds_read_b64 v[230:231], v219 offset:6944
	s_waitcnt lgkmcnt(10)
	v_mfma_f32_16x16x32_bf16 v[124:127], v[232:235], v[224:227], v[124:127]
	ds_read_b64 v[232:233], v219 offset:6976
	ds_read_b64 v[234:235], v219 offset:7008
	s_waitcnt lgkmcnt(10)
	v_mfma_f32_16x16x32_bf16 v[120:123], v[236:239], v[220:223], v[120:123]
	ds_read_b64 v[236:237], v219 offset:9216
	ds_read_b64 v[238:239], v219 offset:9248
	s_waitcnt lgkmcnt(10)
	v_mfma_f32_16x16x32_bf16 v[120:123], v[240:243], v[224:227], v[120:123]
	ds_read_b64 v[240:241], v219 offset:9280
	ds_read_b64 v[242:243], v219 offset:9312
	s_waitcnt lgkmcnt(10)
	v_mfma_f32_16x16x32_bf16 v[116:119], v[128:131], v[220:223], v[116:119]
	ds_read_b64 v[128:129], v219 offset:11520
	ds_read_b64 v[130:131], v219 offset:11552
	s_waitcnt lgkmcnt(10)
	v_mfma_f32_16x16x32_bf16 v[116:119], v[132:135], v[224:227], v[116:119]
	ds_read_b64 v[132:133], v219 offset:11584
	ds_read_b64 v[134:135], v219 offset:11616
	s_waitcnt lgkmcnt(10)
	v_mfma_f32_16x16x32_bf16 v[112:115], v[228:231], v[220:223], v[112:115]
	ds_read_b64 v[228:229], v219 offset:13824
	ds_read_b64 v[230:231], v219 offset:13856
	s_waitcnt lgkmcnt(10)
	v_mfma_f32_16x16x32_bf16 v[112:115], v[232:235], v[224:227], v[112:115]
	ds_read_b64 v[232:233], v219 offset:13888
	ds_read_b64 v[234:235], v219 offset:13920
	s_waitcnt lgkmcnt(10)
	v_mfma_f32_16x16x32_bf16 v[108:111], v[236:239], v[220:223], v[108:111]
	ds_read_b64 v[236:237], v219 offset:16128
	ds_read_b64 v[238:239], v219 offset:16160
	s_waitcnt lgkmcnt(10)
	v_mfma_f32_16x16x32_bf16 v[108:111], v[240:243], v[224:227], v[108:111]
	ds_read_b64 v[240:241], v219 offset:16192
	ds_read_b64 v[242:243], v219 offset:16224
	s_waitcnt lgkmcnt(10)
	v_mfma_f32_16x16x32_bf16 v[96:99], v[128:131], v[220:223], v[96:99]
	ds_read_b64 v[128:129], v219 offset:18432
	ds_read_b64 v[130:131], v219 offset:18464
	s_waitcnt lgkmcnt(10)
	v_mfma_f32_16x16x32_bf16 v[96:99], v[132:135], v[224:227], v[96:99]
	ds_read_b64 v[132:133], v219 offset:18496
	ds_read_b64 v[134:135], v219 offset:18528
	s_waitcnt lgkmcnt(10)
	v_mfma_f32_16x16x32_bf16 v[92:95], v[228:231], v[220:223], v[92:95]
	ds_read_b64 v[228:229], v219 offset:20736
	ds_read_b64 v[230:231], v219 offset:20768
	s_waitcnt lgkmcnt(10)
	v_mfma_f32_16x16x32_bf16 v[92:95], v[232:235], v[224:227], v[92:95]
	ds_read_b64 v[232:233], v219 offset:20800
	ds_read_b64 v[234:235], v219 offset:20832
	s_waitcnt lgkmcnt(10)
	v_mfma_f32_16x16x32_bf16 v[76:79], v[236:239], v[220:223], v[76:79]
	ds_read_b64 v[236:237], v219 offset:23040
	ds_read_b64 v[238:239], v219 offset:23072
	s_waitcnt lgkmcnt(10)
	v_mfma_f32_16x16x32_bf16 v[76:79], v[240:243], v[224:227], v[76:79]
	ds_read_b64 v[240:241], v219 offset:23104
	ds_read_b64 v[242:243], v219 offset:23136
	s_waitcnt lgkmcnt(10)
	v_mfma_f32_16x16x32_bf16 v[68:71], v[128:131], v[220:223], v[68:71]
	ds_read_b64 v[128:129], v219 offset:25344
	ds_read_b64 v[130:131], v219 offset:25376
	s_waitcnt lgkmcnt(10)
	v_mfma_f32_16x16x32_bf16 v[68:71], v[132:135], v[224:227], v[68:71]
	ds_read_b64 v[132:133], v219 offset:25408
	ds_read_b64 v[134:135], v219 offset:25440
	s_waitcnt lgkmcnt(10)
	v_mfma_f32_16x16x32_bf16 v[56:59], v[228:231], v[220:223], v[56:59]
	ds_read_b64 v[228:229], v219 offset:27648
	ds_read_b64 v[230:231], v219 offset:27680
	s_waitcnt lgkmcnt(10)
	v_mfma_f32_16x16x32_bf16 v[56:59], v[232:235], v[224:227], v[56:59]
	ds_read_b64 v[232:233], v219 offset:27712
	ds_read_b64 v[234:235], v219 offset:27744
	s_waitcnt lgkmcnt(10)
	v_mfma_f32_16x16x32_bf16 v[40:43], v[236:239], v[220:223], v[40:43]
	ds_read_b64 v[236:237], v219 offset:29952
	ds_read_b64 v[238:239], v219 offset:29984
	s_waitcnt lgkmcnt(10)
	v_mfma_f32_16x16x32_bf16 v[40:43], v[240:243], v[224:227], v[40:43]
	ds_read_b64 v[240:241], v219 offset:30016
	ds_read_b64 v[242:243], v219 offset:30048
	s_waitcnt lgkmcnt(10)
	v_mfma_f32_16x16x32_bf16 v[16:19], v[128:131], v[220:223], v[16:19]
	ds_read_b64 v[128:129], v219 offset:32256
	ds_read_b64 v[130:131], v219 offset:32288
	s_waitcnt lgkmcnt(10)
	v_mfma_f32_16x16x32_bf16 v[16:19], v[132:135], v[224:227], v[16:19]
	ds_read_b64 v[132:133], v219 offset:32320
	ds_read_b64 v[134:135], v219 offset:32352
	s_waitcnt lgkmcnt(10)
	v_mfma_f32_16x16x32_bf16 v[12:15], v[228:231], v[220:223], v[12:15]
	ds_read_b64 v[228:229], v219 offset:34560
	ds_read_b64 v[230:231], v219 offset:34592
	s_waitcnt lgkmcnt(10)
	v_mfma_f32_16x16x32_bf16 v[12:15], v[232:235], v[224:227], v[12:15]
	ds_read_b64 v[232:233], v219 offset:34624
	ds_read_b64 v[234:235], v219 offset:34656
	s_waitcnt lgkmcnt(10)
	v_mfma_f32_16x16x32_bf16 v[8:11], v[236:239], v[220:223], v[8:11]
	s_waitcnt lgkmcnt(8)
	v_mfma_f32_16x16x32_bf16 v[8:11], v[240:243], v[224:227], v[8:11]
	s_waitcnt lgkmcnt(6)
	v_mfma_f32_16x16x32_bf16 v[4:7], v[128:131], v[220:223], v[4:7]
	s_waitcnt lgkmcnt(4)
	v_mfma_f32_16x16x32_bf16 v[4:7], v[132:135], v[224:227], v[4:7]
	s_waitcnt lgkmcnt(2)
	v_mfma_f32_16x16x32_bf16 v[0:3], v[228:231], v[220:223], v[0:3]
	s_waitcnt lgkmcnt(0)
	v_mfma_f32_16x16x32_bf16 v[0:3], v[232:235], v[224:227], v[0:3]
	v_mov_b32_e32 v129, v171
	s_cmp_lg_u32 s6, 0
	s_cbranch_scc0 .LBB0_2490
	v_mov_b32_e32 v128, v165
	v_mov_b32_e32 v163, v129
	s_branch .LBB0_2492
